# phase 10: hand-written pipelined w_down transposing conversion after the big-tile GEMM (hipcc's phase-10 body skipped on the 512-block grid)
# speedup vs baseline: 1.0221x; 1.0114x over previous
.Lq10_wrapret2:
.Lq10_nonext:
	s_setprio 1
	v_mfma_f32_16x16x32_bf16 v[0:3], v[176:179], v[204:207], v[0:3]
	v_mfma_f32_16x16x32_bf16 v[4:7], v[180:183], v[204:207], v[4:7]
	v_mfma_f32_16x16x32_bf16 v[8:11], v[184:187], v[204:207], v[8:11]
	v_mfma_f32_16x16x32_bf16 v[12:15], v[188:191], v[204:207], v[12:15]
	v_mfma_f32_16x16x32_bf16 v[16:19], v[176:179], v[208:211], v[16:19]
	v_mfma_f32_16x16x32_bf16 v[20:23], v[180:183], v[208:211], v[20:23]
	v_mfma_f32_16x16x32_bf16 v[24:27], v[184:187], v[208:211], v[24:27]
	v_mfma_f32_16x16x32_bf16 v[28:31], v[188:191], v[208:211], v[28:31]
	v_mfma_f32_16x16x32_bf16 v[32:35], v[176:179], v[212:215], v[32:35]
	v_mfma_f32_16x16x32_bf16 v[36:39], v[180:183], v[212:215], v[36:39]
	v_mfma_f32_16x16x32_bf16 v[40:43], v[184:187], v[212:215], v[40:43]
	v_mfma_f32_16x16x32_bf16 v[44:47], v[188:191], v[212:215], v[44:47]
	v_mfma_f32_16x16x32_bf16 v[48:51], v[176:179], v[216:219], v[48:51]
	v_mfma_f32_16x16x32_bf16 v[52:55], v[180:183], v[216:219], v[52:55]
	v_mfma_f32_16x16x32_bf16 v[56:59], v[184:187], v[216:219], v[56:59]
	v_mfma_f32_16x16x32_bf16 v[60:63], v[188:191], v[216:219], v[60:63]
	v_mfma_f32_16x16x32_bf16 v[64:67], v[176:179], v[220:223], v[64:67]
	v_mfma_f32_16x16x32_bf16 v[68:71], v[180:183], v[220:223], v[68:71]
	v_mfma_f32_16x16x32_bf16 v[72:75], v[184:187], v[220:223], v[72:75]
	v_mfma_f32_16x16x32_bf16 v[76:79], v[188:191], v[220:223], v[76:79]
	v_mfma_f32_16x16x32_bf16 v[80:83], v[176:179], v[224:227], v[80:83]
	v_mfma_f32_16x16x32_bf16 v[84:87], v[180:183], v[224:227], v[84:87]
	v_mfma_f32_16x16x32_bf16 v[88:91], v[184:187], v[224:227], v[88:91]
	v_mfma_f32_16x16x32_bf16 v[92:95], v[188:191], v[224:227], v[92:95]
	v_mfma_f32_16x16x32_bf16 v[96:99], v[176:179], v[228:231], v[96:99]
	v_mfma_f32_16x16x32_bf16 v[100:103], v[180:183], v[228:231], v[100:103]
	v_mfma_f32_16x16x32_bf16 v[104:107], v[184:187], v[228:231], v[104:107]
	v_mfma_f32_16x16x32_bf16 v[108:111], v[188:191], v[228:231], v[108:111]
	v_mfma_f32_16x16x32_bf16 v[112:115], v[176:179], v[232:235], v[112:115]
	v_mfma_f32_16x16x32_bf16 v[116:119], v[180:183], v[232:235], v[116:119]
	v_mfma_f32_16x16x32_bf16 v[120:123], v[184:187], v[232:235], v[120:123]
	v_mfma_f32_16x16x32_bf16 v[124:127], v[188:191], v[232:235], v[124:127]
	s_setprio 0
	s_nop 7
	s_and_b32 s51, s90, 63
	s_lshl_b32 s51, s51, 21
	s_lshr_b32 s17, s90, 6
	s_lshl_b32 s17, s17, 9
	s_add_u32 s51, s51, s17
	s_add_u32 s14, s76, s51
	s_addc_u32 s15, s77, 0
	s_add_u32 s16, s92, s51
	s_addc_u32 s17, s93, 0
	s_mov_b32 s18, 0x3f9837f0
	v_lshrrev_b32_e32 v203, 7, v199
	v_and_b32_e32 v238, 15, v199
	v_lshl_add_u32 v203, v203, 7, v238
	v_lshlrev_b32_e32 v203, 13, v203
	v_bfe_u32 v238, v199, 6, 1
	v_lshl_add_u32 v203, v238, 8, v203
	v_bfe_u32 v238, v199, 4, 2
	v_lshl_add_u32 v203, v238, 4, v203
	global_load_dwordx4 v[128:131], v203, s[14:15] offset:0
	global_load_dwordx4 v[132:135], v203, s[14:15] offset:64
	global_load_dwordx4 v[136:139], v203, s[14:15] offset:128
	global_load_dwordx4 v[140:143], v203, s[14:15] offset:192
	s_add_u32 s14, s14, 0x20000
	s_addc_u32 s15, s15, 0
	global_load_dwordx4 v[144:147], v203, s[14:15] offset:0
	global_load_dwordx4 v[148:151], v203, s[14:15] offset:64
	global_load_dwordx4 v[152:155], v203, s[14:15] offset:128
	global_load_dwordx4 v[156:159], v203, s[14:15] offset:192
	s_add_u32 s14, s14, 0x20000
	s_addc_u32 s15, s15, 0
	s_waitcnt vmcnt(4)
	v_fma_f32 v128, s18, v128, v0
	v_fma_f32 v129, s18, v129, v1
	v_fma_f32 v130, s18, v130, v2
	v_fma_f32 v131, s18, v131, v3
	v_fma_f32 v132, s18, v132, v4
	v_fma_f32 v133, s18, v133, v5
	v_fma_f32 v134, s18, v134, v6
	v_fma_f32 v135, s18, v135, v7
	v_fma_f32 v136, s18, v136, v8
	v_fma_f32 v137, s18, v137, v9
	v_fma_f32 v138, s18, v138, v10
	v_fma_f32 v139, s18, v139, v11
	v_fma_f32 v140, s18, v140, v12
	v_fma_f32 v141, s18, v141, v13
	v_fma_f32 v142, s18, v142, v14
	v_fma_f32 v143, s18, v143, v15
	global_store_dwordx4 v203, v[128:131], s[16:17] offset:0
	global_store_dwordx4 v203, v[132:135], s[16:17] offset:64
	global_store_dwordx4 v203, v[136:139], s[16:17] offset:128
	global_store_dwordx4 v203, v[140:143], s[16:17] offset:192
	s_add_u32 s16, s16, 0x20000
	s_addc_u32 s17, s17, 0
	global_load_dwordx4 v[128:131], v203, s[14:15] offset:0
	global_load_dwordx4 v[132:135], v203, s[14:15] offset:64
	global_load_dwordx4 v[136:139], v203, s[14:15] offset:128
	global_load_dwordx4 v[140:143], v203, s[14:15] offset:192
	s_add_u32 s14, s14, 0x20000
	s_addc_u32 s15, s15, 0
	s_waitcnt vmcnt(8)
	v_fma_f32 v144, s18, v144, v16
	v_fma_f32 v145, s18, v145, v17
	v_fma_f32 v146, s18, v146, v18
	v_fma_f32 v147, s18, v147, v19
	v_fma_f32 v148, s18, v148, v20
	v_fma_f32 v149, s18, v149, v21
	v_fma_f32 v150, s18, v150, v22
	v_fma_f32 v151, s18, v151, v23
	v_fma_f32 v152, s18, v152, v24
	v_fma_f32 v153, s18, v153, v25
	v_fma_f32 v154, s18, v154, v26
	v_fma_f32 v155, s18, v155, v27
	v_fma_f32 v156, s18, v156, v28
	v_fma_f32 v157, s18, v157, v29
	v_fma_f32 v158, s18, v158, v30
	v_fma_f32 v159, s18, v159, v31
	global_store_dwordx4 v203, v[144:147], s[16:17] offset:0
	global_store_dwordx4 v203, v[148:151], s[16:17] offset:64
	global_store_dwordx4 v203, v[152:155], s[16:17] offset:128
	global_store_dwordx4 v203, v[156:159], s[16:17] offset:192
	s_add_u32 s16, s16, 0x20000
	s_addc_u32 s17, s17, 0
	global_load_dwordx4 v[144:147], v203, s[14:15] offset:0
	global_load_dwordx4 v[148:151], v203, s[14:15] offset:64
	global_load_dwordx4 v[152:155], v203, s[14:15] offset:128
	global_load_dwordx4 v[156:159], v203, s[14:15] offset:192
	s_add_u32 s14, s14, 0x20000
	s_addc_u32 s15, s15, 0
	s_waitcnt vmcnt(8)
	v_fma_f32 v128, s18, v128, v32
	v_fma_f32 v129, s18, v129, v33
	v_fma_f32 v130, s18, v130, v34
	v_fma_f32 v131, s18, v131, v35
	v_fma_f32 v132, s18, v132, v36
	v_fma_f32 v133, s18, v133, v37
	v_fma_f32 v134, s18, v134, v38
	v_fma_f32 v135, s18, v135, v39
	v_fma_f32 v136, s18, v136, v40
	v_fma_f32 v137, s18, v137, v41
	v_fma_f32 v138, s18, v138, v42
	v_fma_f32 v139, s18, v139, v43
	v_fma_f32 v140, s18, v140, v44
	v_fma_f32 v141, s18, v141, v45
	v_fma_f32 v142, s18, v142, v46
	v_fma_f32 v143, s18, v143, v47
	global_store_dwordx4 v203, v[128:131], s[16:17] offset:0
	global_store_dwordx4 v203, v[132:135], s[16:17] offset:64
	global_store_dwordx4 v203, v[136:139], s[16:17] offset:128
	global_store_dwordx4 v203, v[140:143], s[16:17] offset:192
	s_add_u32 s16, s16, 0x20000
	s_addc_u32 s17, s17, 0
	global_load_dwordx4 v[128:131], v203, s[14:15] offset:0
	global_load_dwordx4 v[132:135], v203, s[14:15] offset:64
	global_load_dwordx4 v[136:139], v203, s[14:15] offset:128
	global_load_dwordx4 v[140:143], v203, s[14:15] offset:192
	s_add_u32 s14, s14, 0x20000
	s_addc_u32 s15, s15, 0
	s_waitcnt vmcnt(8)
	v_fma_f32 v144, s18, v144, v48
	v_fma_f32 v145, s18, v145, v49
	v_fma_f32 v146, s18, v146, v50
	v_fma_f32 v147, s18, v147, v51
	v_fma_f32 v148, s18, v148, v52
	v_fma_f32 v149, s18, v149, v53
	v_fma_f32 v150, s18, v150, v54
	v_fma_f32 v151, s18, v151, v55
	v_fma_f32 v152, s18, v152, v56
	v_fma_f32 v153, s18, v153, v57
	v_fma_f32 v154, s18, v154, v58
	v_fma_f32 v155, s18, v155, v59
	v_fma_f32 v156, s18, v156, v60
	v_fma_f32 v157, s18, v157, v61
	v_fma_f32 v158, s18, v158, v62
	v_fma_f32 v159, s18, v159, v63
	global_store_dwordx4 v203, v[144:147], s[16:17] offset:0
	global_store_dwordx4 v203, v[148:151], s[16:17] offset:64
	global_store_dwordx4 v203, v[152:155], s[16:17] offset:128
	global_store_dwordx4 v203, v[156:159], s[16:17] offset:192
	s_add_u32 s16, s16, 0x20000
	s_addc_u32 s17, s17, 0
	global_load_dwordx4 v[144:147], v203, s[14:15] offset:0
	global_load_dwordx4 v[148:151], v203, s[14:15] offset:64
	global_load_dwordx4 v[152:155], v203, s[14:15] offset:128
	global_load_dwordx4 v[156:159], v203, s[14:15] offset:192
	s_add_u32 s14, s14, 0x20000
	s_addc_u32 s15, s15, 0
	s_waitcnt vmcnt(8)
	v_fma_f32 v128, s18, v128, v64
	v_fma_f32 v129, s18, v129, v65
	v_fma_f32 v130, s18, v130, v66
	v_fma_f32 v131, s18, v131, v67
	v_fma_f32 v132, s18, v132, v68
	v_fma_f32 v133, s18, v133, v69
	v_fma_f32 v134, s18, v134, v70
	v_fma_f32 v135, s18, v135, v71
	v_fma_f32 v136, s18, v136, v72
	v_fma_f32 v137, s18, v137, v73
	v_fma_f32 v138, s18, v138, v74
	v_fma_f32 v139, s18, v139, v75
	v_fma_f32 v140, s18, v140, v76
	v_fma_f32 v141, s18, v141, v77
	v_fma_f32 v142, s18, v142, v78
	v_fma_f32 v143, s18, v143, v79
	global_store_dwordx4 v203, v[128:131], s[16:17] offset:0
	global_store_dwordx4 v203, v[132:135], s[16:17] offset:64
	global_store_dwordx4 v203, v[136:139], s[16:17] offset:128
	global_store_dwordx4 v203, v[140:143], s[16:17] offset:192
	s_add_u32 s16, s16, 0x20000
	s_addc_u32 s17, s17, 0
	global_load_dwordx4 v[128:131], v203, s[14:15] offset:0
	global_load_dwordx4 v[132:135], v203, s[14:15] offset:64
	global_load_dwordx4 v[136:139], v203, s[14:15] offset:128
	global_load_dwordx4 v[140:143], v203, s[14:15] offset:192
	s_add_u32 s14, s14, 0x20000
	s_addc_u32 s15, s15, 0
	s_waitcnt vmcnt(8)
	v_fma_f32 v144, s18, v144, v80
	v_fma_f32 v145, s18, v145, v81
	v_fma_f32 v146, s18, v146, v82
	v_fma_f32 v147, s18, v147, v83
	v_fma_f32 v148, s18, v148, v84
	v_fma_f32 v149, s18, v149, v85
	v_fma_f32 v150, s18, v150, v86
	v_fma_f32 v151, s18, v151, v87
	v_fma_f32 v152, s18, v152, v88
	v_fma_f32 v153, s18, v153, v89
	v_fma_f32 v154, s18, v154, v90
	v_fma_f32 v155, s18, v155, v91
	v_fma_f32 v156, s18, v156, v92
	v_fma_f32 v157, s18, v157, v93
	v_fma_f32 v158, s18, v158, v94
	v_fma_f32 v159, s18, v159, v95
	global_store_dwordx4 v203, v[144:147], s[16:17] offset:0
	global_store_dwordx4 v203, v[148:151], s[16:17] offset:64
	global_store_dwordx4 v203, v[152:155], s[16:17] offset:128
	global_store_dwordx4 v203, v[156:159], s[16:17] offset:192
	s_add_u32 s16, s16, 0x20000
	s_addc_u32 s17, s17, 0
	global_load_dwordx4 v[144:147], v203, s[14:15] offset:0
	global_load_dwordx4 v[148:151], v203, s[14:15] offset:64
	global_load_dwordx4 v[152:155], v203, s[14:15] offset:128
	global_load_dwordx4 v[156:159], v203, s[14:15] offset:192
	s_add_u32 s14, s14, 0x20000
	s_addc_u32 s15, s15, 0
	s_waitcnt vmcnt(8)
	v_fma_f32 v128, s18, v128, v96
	v_fma_f32 v129, s18, v129, v97
	v_fma_f32 v130, s18, v130, v98
	v_fma_f32 v131, s18, v131, v99
	v_fma_f32 v132, s18, v132, v100
	v_fma_f32 v133, s18, v133, v101
	v_fma_f32 v134, s18, v134, v102
	v_fma_f32 v135, s18, v135, v103
	v_fma_f32 v136, s18, v136, v104
	v_fma_f32 v137, s18, v137, v105
	v_fma_f32 v138, s18, v138, v106
	v_fma_f32 v139, s18, v139, v107
	v_fma_f32 v140, s18, v140, v108
	v_fma_f32 v141, s18, v141, v109
	v_fma_f32 v142, s18, v142, v110
	v_fma_f32 v143, s18, v143, v111
	global_store_dwordx4 v203, v[128:131], s[16:17] offset:0
	global_store_dwordx4 v203, v[132:135], s[16:17] offset:64
	global_store_dwordx4 v203, v[136:139], s[16:17] offset:128
	global_store_dwordx4 v203, v[140:143], s[16:17] offset:192
	s_add_u32 s16, s16, 0x20000
	s_addc_u32 s17, s17, 0
	s_waitcnt vmcnt(4)
	v_fma_f32 v144, s18, v144, v112
	v_fma_f32 v145, s18, v145, v113
	v_fma_f32 v146, s18, v146, v114
	v_fma_f32 v147, s18, v147, v115
	v_fma_f32 v148, s18, v148, v116
	v_fma_f32 v149, s18, v149, v117
	v_fma_f32 v150, s18, v150, v118
	v_fma_f32 v151, s18, v151, v119
	v_fma_f32 v152, s18, v152, v120
	v_fma_f32 v153, s18, v153, v121
	v_fma_f32 v154, s18, v154, v122
	v_fma_f32 v155, s18, v155, v123
	v_fma_f32 v156, s18, v156, v124
	v_fma_f32 v157, s18, v157, v125
	v_fma_f32 v158, s18, v158, v126
	v_fma_f32 v159, s18, v159, v127
	global_store_dwordx4 v203, v[144:147], s[16:17] offset:0
	global_store_dwordx4 v203, v[148:151], s[16:17] offset:64
	global_store_dwordx4 v203, v[152:155], s[16:17] offset:128
	global_store_dwordx4 v203, v[156:159], s[16:17] offset:192
	s_add_u32 s16, s16, 0x20000
	s_addc_u32 s17, s17, 0
	s_add_u32 s90, s90, 0x200
	s_cmp_lt_u32 s90, 0x400
	s_cbranch_scc1 .Lq10_tile
	s_waitcnt vmcnt(0)
	s_barrier
	v_readlane_b32 s52, v242, 43
	v_readlane_b32 s53, v242, 44
	v_lshrrev_b32_e32 v240, 2, v199
	v_and_b32_e32 v241, 3, v199
	v_lshlrev_b32_e32 v236, 13, v240
	v_lshl_add_u32 v236, v241, 6, v236
	v_mul_u32_u24_e32 v237, 0x900, v241
	v_lshl_add_u32 v237, v240, 1, v237
	v_mul_u32_u24_e32 v238, 0x90, v240
	v_lshl_add_u32 v238, v241, 5, v238
	v_lshlrev_b32_e32 v239, 10, v240
	v_lshl_add_u32 v239, v241, 5, v239
	s_mov_b32 s50, s58
	s_lshr_b32 s22, s50, 8
	s_bfe_u32 s23, s50, 0x30005
	s_and_b32 s25, s50, 31
	s_lshl_b32 s26, s22, 22
	s_lshl_b32 s27, s23, 19
	s_add_u32 s26, s26, s27
	s_lshl_b32 s27, s25, 8
	s_add_u32 s26, s26, s27
	s_add_u32 s36, s52, s26
	s_addc_u32 s37, s53, 0
	s_lshl_b32 s26, s22, 21
	s_lshl_b32 s27, s25, 16
	s_add_u32 s26, s26, s27
	s_lshl_b32 s27, s23, 7
	s_add_u32 s26, s26, s27
	s_add_u32 s40, s94, s26
	s_addc_u32 s41, s95, 0
	s_add_u32 s40, s40, 0x6c00000
	s_addc_u32 s41, s41, 0
	global_load_dwordx4 v[128:131], v236, s[36:37]
	global_load_dwordx4 v[132:135], v236, s[36:37] offset:16
	global_load_dwordx4 v[136:139], v236, s[36:37] offset:32
	global_load_dwordx4 v[140:143], v236, s[36:37] offset:48
	s_mov_b32 s51, 0
.Lwdt_loop:
	s_add_u32 s50, s50, 0x200
	s_lshr_b32 s22, s50, 8
	s_bfe_u32 s23, s50, 0x30005
	s_and_b32 s25, s50, 31
	s_lshl_b32 s26, s22, 22
	s_lshl_b32 s27, s23, 19
	s_add_u32 s26, s26, s27
	s_lshl_b32 s27, s25, 8
	s_add_u32 s26, s26, s27
	s_add_u32 s44, s52, s26
	s_addc_u32 s45, s53, 0
	s_lshl_b32 s26, s22, 21
	s_lshl_b32 s27, s25, 16
	s_add_u32 s26, s26, s27
	s_lshl_b32 s27, s23, 7
	s_add_u32 s26, s26, s27
	s_add_u32 s46, s94, s26
	s_addc_u32 s47, s95, 0
	s_add_u32 s46, s46, 0x6c00000
	s_addc_u32 s47, s47, 0
	global_load_dwordx4 v[144:147], v236, s[44:45]
	global_load_dwordx4 v[148:151], v236, s[44:45] offset:16
	global_load_dwordx4 v[152:155], v236, s[44:45] offset:32
	global_load_dwordx4 v[156:159], v236, s[44:45] offset:48
	s_waitcnt vmcnt(4)
	v_cvt_pk_bf16_f32 v160, v128, v129
	v_cvt_pk_bf16_f32 v161, v130, v131
	v_cvt_pk_bf16_f32 v162, v132, v133
	v_cvt_pk_bf16_f32 v163, v134, v135
	v_cvt_pk_bf16_f32 v164, v136, v137
	v_cvt_pk_bf16_f32 v165, v138, v139
	v_cvt_pk_bf16_f32 v166, v140, v141
	v_cvt_pk_bf16_f32 v167, v142, v143
	ds_write_b16 v237, v160 offset:0
	ds_write_b16_d16_hi v237, v160 offset:144
	ds_write_b16 v237, v161 offset:288
	ds_write_b16_d16_hi v237, v161 offset:432
	ds_write_b16 v237, v162 offset:576
	ds_write_b16_d16_hi v237, v162 offset:720
	ds_write_b16 v237, v163 offset:864
	ds_write_b16_d16_hi v237, v163 offset:1008
	ds_write_b16 v237, v164 offset:1152
	ds_write_b16_d16_hi v237, v164 offset:1296
	ds_write_b16 v237, v165 offset:1440
	ds_write_b16_d16_hi v237, v165 offset:1584
	ds_write_b16 v237, v166 offset:1728
	ds_write_b16_d16_hi v237, v166 offset:1872
	ds_write_b16 v237, v167 offset:2016
	ds_write_b16_d16_hi v237, v167 offset:2160
	s_waitcnt lgkmcnt(0)
	s_barrier
	ds_read_b128 v[168:171], v238 offset:0
	ds_read_b128 v[172:175], v238 offset:16
	s_waitcnt lgkmcnt(0)
	global_store_dwordx4 v239, v[168:171], s[40:41]
	global_store_dwordx4 v239, v[172:175], s[40:41] offset:16
	s_add_u32 s50, s50, 0x200
	s_cmp_eq_u32 s51, 7
	s_cbranch_scc1 .Lwdt_last
	s_lshr_b32 s22, s50, 8
	s_bfe_u32 s23, s50, 0x30005
	s_and_b32 s25, s50, 31
	s_lshl_b32 s26, s22, 22
	s_lshl_b32 s27, s23, 19
	s_add_u32 s26, s26, s27
	s_lshl_b32 s27, s25, 8
	s_add_u32 s26, s26, s27
	s_add_u32 s36, s52, s26
	s_addc_u32 s37, s53, 0
	s_lshl_b32 s26, s22, 21
	s_lshl_b32 s27, s25, 16
	s_add_u32 s26, s26, s27
	s_lshl_b32 s27, s23, 7
	s_add_u32 s26, s26, s27
	s_add_u32 s40, s94, s26
	s_addc_u32 s41, s95, 0
	s_add_u32 s40, s40, 0x6c00000
	s_addc_u32 s41, s41, 0
	global_load_dwordx4 v[128:131], v236, s[36:37]
	global_load_dwordx4 v[132:135], v236, s[36:37] offset:16
	global_load_dwordx4 v[136:139], v236, s[36:37] offset:32
	global_load_dwordx4 v[140:143], v236, s[36:37] offset:48
	s_waitcnt vmcnt(4)
	v_cvt_pk_bf16_f32 v160, v144, v145
	v_cvt_pk_bf16_f32 v161, v146, v147
	v_cvt_pk_bf16_f32 v162, v148, v149
	v_cvt_pk_bf16_f32 v163, v150, v151
	v_cvt_pk_bf16_f32 v164, v152, v153
	v_cvt_pk_bf16_f32 v165, v154, v155
	v_cvt_pk_bf16_f32 v166, v156, v157
	v_cvt_pk_bf16_f32 v167, v158, v159
	ds_write_b16 v237, v160 offset:9216
	ds_write_b16_d16_hi v237, v160 offset:9360
	ds_write_b16 v237, v161 offset:9504
	ds_write_b16_d16_hi v237, v161 offset:9648
	ds_write_b16 v237, v162 offset:9792
	ds_write_b16_d16_hi v237, v162 offset:9936
	ds_write_b16 v237, v163 offset:10080
	ds_write_b16_d16_hi v237, v163 offset:10224
	ds_write_b16 v237, v164 offset:10368
	ds_write_b16_d16_hi v237, v164 offset:10512
	ds_write_b16 v237, v165 offset:10656
	ds_write_b16_d16_hi v237, v165 offset:10800
	ds_write_b16 v237, v166 offset:10944
	ds_write_b16_d16_hi v237, v166 offset:11088
	ds_write_b16 v237, v167 offset:11232
	ds_write_b16_d16_hi v237, v167 offset:11376
	s_waitcnt lgkmcnt(0)
	s_barrier
	ds_read_b128 v[168:171], v238 offset:9216
	ds_read_b128 v[172:175], v238 offset:9232
	s_waitcnt lgkmcnt(0)
	global_store_dwordx4 v239, v[168:171], s[46:47]
	global_store_dwordx4 v239, v[172:175], s[46:47] offset:16
	s_add_u32 s51, s51, 1
	s_branch .Lwdt_loop
.Lwdt_last:
	s_waitcnt vmcnt(0)
	v_cvt_pk_bf16_f32 v160, v144, v145
	v_cvt_pk_bf16_f32 v161, v146, v147
	v_cvt_pk_bf16_f32 v162, v148, v149
	v_cvt_pk_bf16_f32 v163, v150, v151
	v_cvt_pk_bf16_f32 v164, v152, v153
	v_cvt_pk_bf16_f32 v165, v154, v155
	v_cvt_pk_bf16_f32 v166, v156, v157
	v_cvt_pk_bf16_f32 v167, v158, v159
	ds_write_b16 v237, v160 offset:9216
	ds_write_b16_d16_hi v237, v160 offset:9360
	ds_write_b16 v237, v161 offset:9504
	ds_write_b16_d16_hi v237, v161 offset:9648
	ds_write_b16 v237, v162 offset:9792
	ds_write_b16_d16_hi v237, v162 offset:9936
	ds_write_b16 v237, v163 offset:10080
	ds_write_b16_d16_hi v237, v163 offset:10224
	ds_write_b16 v237, v164 offset:10368
	ds_write_b16_d16_hi v237, v164 offset:10512
	ds_write_b16 v237, v165 offset:10656
	ds_write_b16_d16_hi v237, v165 offset:10800
	ds_write_b16 v237, v166 offset:10944
	ds_write_b16_d16_hi v237, v166 offset:11088
	ds_write_b16 v237, v167 offset:11232
	ds_write_b16_d16_hi v237, v167 offset:11376
	s_waitcnt lgkmcnt(0)
	s_barrier
	ds_read_b128 v[168:171], v238 offset:9216
	ds_read_b128 v[172:175], v238 offset:9232
	s_waitcnt lgkmcnt(0)
	global_store_dwordx4 v239, v[168:171], s[46:47]
	global_store_dwordx4 v239, v[172:175], s[46:47] offset:16
	s_waitcnt vmcnt(0)
	s_branch .LBB0_808
